# non-temporal hint on the f32 residual-stream loads and stores of the w_out and mlp2 GEMM epilogues (each line touched once)
# baseline (speedup 1.0000x reference)
; DEVI const float* modrow(const Params& p, int l, int row) { const int bi = row < NLAT ? (row >> 11) : 16; return (const float*)(p.ws + OFF_MOD) + (size_t)(l * 17 + bi) * 6144; }
;     DEVI void operator()(f32x4 (&acc)[2][2][4][2], const Unit& u, int wr, int wc, int fr, int fq) const {
;         const int row0 = u.pm * BM + wr * 64 + fr, col0 = u.pn * BM + wc * 32 + 4 * fq;
;         const float* gr = modrow(p, l, u.pm * BM) + goff + col0;
;         f32x4 gv[2][2];
; #pragma unroll
;         for (int bj = 0; bj < 2; ++bj)
; #pragma unroll
;             for (int n = 0; n < 2; ++n) gv[bj][n] = *(const f32x4*)(gr + bj * HALF + n * 16);
;         f32x4 av[2][2];
;         if (emit) { const int bi = u.pm * BM < NLAT ? (u.pm * BM) >> 11 : 16; const float* ar = (const float*)(p.ws + OFF_A2) + (size_t)(l * 17 + bi) * 1024 + col0;
; #pragma unroll
;             for (int bj = 0; bj < 2; ++bj)
; #pragma unroll
;                 for (int n = 0; n < 2; ++n) av[bj][n] = *(const f32x4*)(ar + bj * HALF + n * 16); }
; #pragma unroll
;         for (int am = 0; am < 4; ++am) {
;             const int ai = am >> 1, mb = (am & 1) * 2;
;             f32x4 xv[2][2][2];
; #pragma unroll
;             for (int mm = 0; mm < 2; ++mm) { const int r = row0 + ai * HALF + (mb + mm) * 16;
;                 const float* xi = (in_is_stream ? (const float*)xrow_out(p, r) : xrow_in(p, l, r)) + col0;
; #pragma unroll
;                 for (int bj = 0; bj < 2; ++bj)
; #pragma unroll
;                     for (int n = 0; n < 2; ++n) xv[mm][bj][n] = *(const f32x4*)(xi + bj * HALF + n * 16); }
.Lzp_epi_2:
	s_lshl_b32 s6, s2, 8
	s_min_i32 s3, s6, 0x8000
	s_ashr_i32 s3, s3, 11
	s_add_i32 s3, s3, s59
	s_mul_hi_i32 s5, s3, 0x6000
	s_mulk_i32 s3, 0x6000
	v_lshl_or_b32 v206, s4, 8, v215
	s_add_u32 s4, s24, s3
	s_addc_u32 s5, s25, s5
	v_ashrrev_i32_e32 v207, 31, v206
	s_min_i32 s2, s2, 0x80
	v_lshlrev_b64 v[210:211], 2, v[206:207]
	s_ashr_i32 s2, s2, 3
	v_lshl_add_u64 v[54:55], s[4:5], 0, v[210:211]
	s_mov_b64 s[4:5], 0x1e082000
	s_mov_b32 s3, 0x1e082000
	s_add_i32 s2, s2, s59
	v_lshl_add_u64 v[56:57], v[54:55], 0, s[4:5]
	v_add_co_u32_e32 v54, vcc, s3, v54
	s_ashr_i32 s3, s2, 31
	s_lshl_b64 s[2:3], s[2:3], 12
	v_readlane_b32 s4, v252, 40
	v_readlane_b32 s5, v252, 41
	s_add_u32 s2, s4, s2
	v_addc_co_u32_e32 v55, vcc, 0, v55, vcc
	s_addc_u32 s3, s5, s3
	global_load_dwordx4 v[74:77], v[56:57], off offset:64 nt
	global_load_dwordx4 v[66:69], v[56:57], off offset:512 nt
	global_load_dwordx4 v[86:89], v[54:55], off nt
	global_load_dwordx4 v[58:61], v[56:57], off offset:576 nt
	v_lshl_add_u64 v[54:55], s[2:3], 0, v[210:211]
	global_load_dwordx4 v[90:93], v[54:55], off nt
	global_load_dwordx4 v[78:81], v[54:55], off offset:64 nt
	global_load_dwordx4 v[70:73], v[54:55], off offset:512 nt
	s_nop 0
	global_load_dwordx4 v[54:57], v[54:55], off offset:576 nt
	v_add_u32_e32 v208, s6, v199
	s_mov_b32 s2, 0x8000
	v_readlane_b32 s38, v253, 33
	v_cmp_gt_i32_e64 s[4:5], s2, v208
	s_movk_i32 s2, 0x7fff
	v_readlane_b32 s39, v253, 34
	v_cmp_lt_i32_e64 s[2:3], s2, v208
	s_mov_b64 s[6:7], -1
	s_and_b64 vcc, exec, s[38:39]
	s_cbranch_vccz .LBB0_1080
	v_mov_b64_e32 v[162:163], s[22:23]
	s_and_saveexec_b64 s[6:7], s[2:3]
	s_xor_b64 s[6:7], exec, s[6:7]
	v_add_u32_e32 v0, 0xffff8000, v208
	v_mov_b64_e32 v[162:163], s[16:17]
	v_mov_b64_e32 v[164:165], v[0:1]
	s_andn2_saveexec_b64 s[6:7], s[6:7]
	v_ashrrev_i32_e32 v209, 31, v208
	v_mov_b64_e32 v[164:165], v[208:209]
	s_or_b64 exec, exec, s[6:7]
	s_mov_b64 s[6:7], 0

;     DEVI void operator()(f32x4 (&acc)[2][2][4][2], const Unit& u, int wr, int wc, int fr, int fq) const {
;     ...
;             for (int mm = 0; mm < 2; ++mm) { const int r = row0 + ai * HALF + (mb + mm) * 16;
;                 const float* xi = (in_is_stream ? (const float*)xrow_out(p, r) : xrow_in(p, l, r)) + col0;
; #pragma unroll
;                 for (int bj = 0; bj < 2; ++bj)
; #pragma unroll
;                     for (int n = 0; n < 2; ++n) xv[mm][bj][n] = *(const f32x4*)(xi + bj * HALF + n * 16); }
.LBB0_1086:
	v_lshlrev_b64 v[164:165], 12, v[164:165]
	v_lshl_add_u64 v[162:163], v[162:163], 0, v[164:165]
	v_lshl_add_u64 v[162:163], v[206:207], 2, v[162:163]
	global_load_dwordx4 v[190:193], v[162:163], off nt
	global_load_dwordx4 v[186:189], v[162:163], off offset:64 nt
	global_load_dwordx4 v[174:177], v[162:163], off offset:512 nt
	global_load_dwordx4 v[166:169], v[162:163], off offset:576 nt
	v_or_b32_e32 v212, 16, v208
	s_mov_b32 s2, 0x8000
	s_movk_i32 s6, 0x7fff
	v_cmp_gt_i32_e64 s[2:3], s2, v212
	v_cmp_lt_i32_e64 s[6:7], s6, v212
	s_and_b64 vcc, exec, s[34:35]
	s_mov_b64 s[38:39], -1
	s_cbranch_vccnz .LBB0_1092
	v_mov_b64_e32 v[162:163], s[22:23]
	s_and_saveexec_b64 s[38:39], s[6:7]
	s_xor_b64 s[38:39], exec, s[38:39]
	v_add_u32_e32 v0, 0xffff8010, v208
	v_mov_b64_e32 v[162:163], s[16:17]
	v_mov_b64_e32 v[164:165], v[0:1]
	s_andn2_saveexec_b64 s[38:39], s[38:39]
	v_ashrrev_i32_e32 v213, 31, v212
	v_mov_b64_e32 v[164:165], v[212:213]
	s_or_b64 exec, exec, s[38:39]
	s_mov_b64 s[38:39], 0

; DEVI unsigned cvt_pk_bf16(float lo, float hi) { unsigned r; asm volatile("v_cvt_pk_bf16_f32 %0, %1, %2" : "=v"(r) : "v"(lo), "v"(hi)); return r; }
;     DEVI void operator()(f32x4 (&acc)[2][2][4][2], const Unit& u, int wr, int wc, int fr, int fq) const {
;     ...
;             for (int mm = 0; mm < 2; ++mm) { const int r = row0 + ai * HALF + (mb + mm) * 16;
;                 const float* xi = (in_is_stream ? (const float*)xrow_out(p, r) : xrow_in(p, l, r)) + col0;
; #pragma unroll
;                 for (int bj = 0; bj < 2; ++bj)
; #pragma unroll
;                     for (int n = 0; n < 2; ++n) xv[mm][bj][n] = *(const f32x4*)(xi + bj * HALF + n * 16); }
; #pragma unroll
;             for (int mm = 0; mm < 2; ++mm) { const int m = mb + mm; const int r = row0 + ai * HALF + m * 16; float* xo = xrow_out(p, r) + col0;
;                 float ssp = 0.f;
; #pragma unroll
;                 for (int bj = 0; bj < 2; ++bj)
; #pragma unroll
;                     for (int n = 0; n < 2; ++n) { const f32x4 xn = xv[mm][bj][n] + gv[bj][n] * acc[ai][bj][m][n]; *(f32x4*)(xo + bj * HALF + n * 16) = xn;
;                         if (emit) { ssp += xn[0] * xn[0] + xn[1] * xn[1] + xn[2] * xn[2] + xn[3] * xn[3];
;                             const f32x4 ua = xn * av[bj][n]; u32x2 w; w.x = cvt_pk_bf16(ua[0], ua[1]); w.y = cvt_pk_bf16(ua[2], ua[3]);
;                             *(u32x2*)((bf16_t*)(p.ws + OFF_U2) + (size_t)r * DM + col0 + bj * HALF + n * 16) = w; } }
;                 if (emit) { ssp += __shfl_xor(ssp, 16); ssp += __shfl_xor(ssp, 32); if (fq == 0) atomicAdd((float*)(p.ws + OFF_SSQ2) + (size_t)l * RT_ + r, ssp); } }
.LBB0_1098:
	v_lshlrev_b64 v[164:165], 12, v[164:165]
	v_lshl_add_u64 v[162:163], v[162:163], 0, v[164:165]
	v_lshl_add_u64 v[162:163], v[162:163], 0, v[210:211]
	global_load_dwordx4 v[182:185], v[162:163], off nt
	global_load_dwordx4 v[178:181], v[162:163], off offset:64 nt
	global_load_dwordx4 v[170:173], v[162:163], off offset:512 nt
	s_nop 0
	global_load_dwordx4 v[162:165], v[162:163], off offset:576 nt
	v_add_u32_e32 v0, 0xffff8000, v208
	v_ashrrev_i32_e32 v209, 31, v208
	v_cndmask_b32_e64 v218, v0, v208, s[4:5]
	v_mov_b32_e32 v0, s17
	v_mov_b32_e32 v213, s23
	v_cndmask_b32_e64 v219, 0, v209, s[4:5]
	v_cndmask_b32_e64 v221, v0, v213, s[4:5]
	v_mov_b32_e32 v0, s16
	v_mov_b32_e32 v213, s22
	s_waitcnt vmcnt(0)
	v_pk_fma_f32 v[158:159], v[158:159], v[86:87], v[190:191]
	v_cndmask_b32_e64 v220, v0, v213, s[4:5]
	v_lshlrev_b64 v[218:219], 12, v[218:219]
	v_mul_f32_e32 v0, v159, v159
	v_lshl_add_u64 v[218:219], v[220:221], 0, v[218:219]
	v_pk_fma_f32 v[160:161], v[160:161], v[88:89], v[192:193]
	v_fmac_f32_e32 v0, v158, v158
	v_lshl_add_u64 v[218:219], v[218:219], 0, v[210:211]
	v_fmac_f32_e32 v0, v160, v160
	v_lshlrev_b64 v[220:221], 11, v[208:209]
	global_store_dwordx4 v[218:219], v[158:161], off nt
	v_fmac_f32_e32 v0, v161, v161
	v_pk_fma_f32 v[154:155], v[154:155], v[74:75], v[186:187]
	v_pk_mul_f32 v[160:161], v[92:93], v[160:161]
	v_pk_mul_f32 v[158:159], v[90:91], v[158:159]
	v_pk_fma_f32 v[156:157], v[156:157], v[76:77], v[188:189]
	v_cvt_pk_bf16_f32 v158, v158, v159
	v_cvt_pk_bf16_f32 v159, v160, v161
	v_lshl_add_u64 v[160:161], s[24:25], 0, v[220:221]
	v_lshl_add_u64 v[160:161], v[206:207], 1, v[160:161]
	global_store_dwordx2 v[160:161], v[158:159], off
	v_mul_f32_e32 v158, v155, v155
	global_store_dwordx4 v[218:219], v[154:157], off offset:64 nt
	v_fmac_f32_e32 v158, v154, v154
	v_fmac_f32_e32 v158, v156, v156
	v_pk_mul_f32 v[154:155], v[78:79], v[154:155]
	v_pk_fma_f32 v[150:151], v[150:151], v[66:67], v[174:175]
	v_cvt_pk_bf16_f32 v154, v154, v155
	v_fmac_f32_e32 v158, v157, v157
	v_pk_mul_f32 v[156:157], v[80:81], v[156:157]
	v_pk_fma_f32 v[152:153], v[152:153], v[68:69], v[176:177]
	v_cvt_pk_bf16_f32 v155, v156, v157
	global_store_dwordx2 v[160:161], v[154:155], off offset:32
	v_mul_f32_e32 v154, v151, v151
	v_fmac_f32_e32 v154, v150, v150
	v_fmac_f32_e32 v154, v152, v152
	global_store_dwordx4 v[218:219], v[150:153], off offset:512 nt
	v_fmac_f32_e32 v154, v153, v153
	v_pk_fma_f32 v[146:147], v[146:147], v[58:59], v[166:167]
	v_pk_mul_f32 v[152:153], v[72:73], v[152:153]
	v_pk_mul_f32 v[150:151], v[70:71], v[150:151]
	v_pk_fma_f32 v[148:149], v[148:149], v[60:61], v[168:169]
	v_cvt_pk_bf16_f32 v150, v150, v151
	v_cvt_pk_bf16_f32 v151, v152, v153
	v_mul_f32_e32 v152, v147, v147
	v_fmac_f32_e32 v152, v146, v146
	v_add_f32_e32 v0, v0, v158
	v_fmac_f32_e32 v152, v148, v148
	v_add_f32_e32 v0, v0, v154
	v_fmac_f32_e32 v152, v149, v149
	v_cmp_lt_i32_e32 vcc, v228, v226
	v_add_f32_e32 v0, v0, v152
	global_store_dwordx2 v[160:161], v[150:151], off offset:256
	global_store_dwordx4 v[218:219], v[146:149], off offset:576 nt
	v_cndmask_b32_e32 v152, v225, v228, vcc
	v_lshlrev_b32_e32 v168, 2, v152
	ds_bpermute_b32 v152, v168, v0
	v_cmp_lt_i32_e32 vcc, v227, v226
	v_pk_mul_f32 v[150:151], v[54:55], v[146:147]
	v_lshl_add_u64 v[166:167], v[208:209], 2, s[8:9]
	v_cndmask_b32_e32 v146, v225, v227, vcc
	s_waitcnt lgkmcnt(0)
	v_add_f32_e32 v0, v0, v152
	v_lshlrev_b32_e32 v169, 2, v146
	ds_bpermute_b32 v146, v169, v0
	v_pk_mul_f32 v[148:149], v[56:57], v[148:149]
	v_cvt_pk_bf16_f32 v150, v150, v151
	s_nop 0
	v_cvt_pk_bf16_f32 v151, v148, v149
	global_store_dwordx2 v[160:161], v[150:151], off offset:288
	s_and_saveexec_b64 s[4:5], s[0:1]
	s_cbranch_execz .LBB0_1100
	s_waitcnt lgkmcnt(0)
	v_add_f32_e32 v0, v0, v146
	global_atomic_add_f32 v[166:167], v0, off
.LBB0_1100:
	s_or_b64 exec, exec, s[4:5]
	v_add_u32_e32 v0, 0xffff8010, v208
	v_ashrrev_i32_e32 v213, 31, v212
	s_waitcnt lgkmcnt(0)
	v_cndmask_b32_e64 v146, v0, v212, s[2:3]
	v_mov_b32_e32 v0, s17
	v_mov_b32_e32 v148, s23
	v_cndmask_b32_e64 v147, 0, v213, s[2:3]
	v_cndmask_b32_e64 v149, v0, v148, s[2:3]
	v_mov_b32_e32 v0, s16
	v_mov_b32_e32 v148, s22
	v_pk_fma_f32 v[142:143], v[142:143], v[86:87], v[182:183]
	v_cndmask_b32_e64 v148, v0, v148, s[2:3]
	v_lshlrev_b64 v[146:147], 12, v[146:147]
	v_mul_f32_e32 v0, v143, v143
	v_lshl_add_u64 v[146:147], v[148:149], 0, v[146:147]
	v_pk_fma_f32 v[144:145], v[144:145], v[88:89], v[184:185]
	v_fmac_f32_e32 v0, v142, v142
	v_lshl_add_u64 v[146:147], v[206:207], 2, v[146:147]
	v_fmac_f32_e32 v0, v144, v144
	v_lshlrev_b64 v[148:149], 11, v[212:213]
	global_store_dwordx4 v[146:147], v[142:145], off nt
	v_fmac_f32_e32 v0, v145, v145
	v_pk_fma_f32 v[138:139], v[138:139], v[74:75], v[178:179]
	v_pk_mul_f32 v[144:145], v[92:93], v[144:145]
	v_pk_mul_f32 v[142:143], v[90:91], v[142:143]
	v_pk_fma_f32 v[140:141], v[140:141], v[76:77], v[180:181]
	v_cvt_pk_bf16_f32 v142, v142, v143
	v_cvt_pk_bf16_f32 v143, v144, v145
	v_lshl_add_u64 v[144:145], s[24:25], 0, v[148:149]
	v_lshl_add_u64 v[144:145], v[206:207], 1, v[144:145]
	global_store_dwordx2 v[144:145], v[142:143], off
	v_mul_f32_e32 v142, v139, v139
	global_store_dwordx4 v[146:147], v[138:141], off offset:64 nt
	v_fmac_f32_e32 v142, v138, v138
	v_fmac_f32_e32 v142, v140, v140
	v_pk_mul_f32 v[138:139], v[78:79], v[138:139]
	v_pk_fma_f32 v[134:135], v[134:135], v[66:67], v[170:171]
	v_cvt_pk_bf16_f32 v138, v138, v139
	v_fmac_f32_e32 v142, v141, v141
	v_pk_mul_f32 v[140:141], v[80:81], v[140:141]
	v_pk_fma_f32 v[136:137], v[136:137], v[68:69], v[172:173]
	v_cvt_pk_bf16_f32 v139, v140, v141
	global_store_dwordx2 v[144:145], v[138:139], off offset:32
	v_mul_f32_e32 v138, v135, v135
	v_fmac_f32_e32 v138, v134, v134
	v_fmac_f32_e32 v138, v136, v136
	v_add_f32_e32 v0, v0, v142
	global_store_dwordx4 v[146:147], v[134:137], off offset:512 nt
	v_fmac_f32_e32 v138, v137, v137
	v_add_f32_e32 v0, v0, v138
	v_pk_mul_f32 v[134:135], v[70:71], v[134:135]
	v_pk_mul_f32 v[136:137], v[72:73], v[136:137]
	v_cvt_pk_bf16_f32 v138, v134, v135
	v_pk_fma_f32 v[134:135], v[132:133], v[60:61], v[164:165]
	v_pk_fma_f32 v[132:133], v[130:131], v[58:59], v[162:163]
	v_cvt_pk_bf16_f32 v139, v136, v137
	global_store_dwordx2 v[144:145], v[138:139], off offset:256
	global_store_dwordx4 v[146:147], v[132:135], off offset:576 nt
	v_mul_f32_e32 v130, v133, v133
	v_fmac_f32_e32 v130, v132, v132
	v_fmac_f32_e32 v130, v134, v134
	v_fmac_f32_e32 v130, v135, v135
	v_add_f32_e32 v0, v0, v130
	ds_bpermute_b32 v130, v168, v0
	v_pk_mul_f32 v[132:133], v[54:55], v[132:133]
	v_pk_mul_f32 v[134:135], v[56:57], v[134:135]
	v_cvt_pk_bf16_f32 v132, v132, v133
	s_waitcnt lgkmcnt(0)
	v_add_f32_e32 v0, v0, v130
	ds_bpermute_b32 v130, v169, v0
	v_cvt_pk_bf16_f32 v133, v134, v135
	global_store_dwordx2 v[144:145], v[132:133], off offset:288
	s_and_saveexec_b64 s[2:3], s[0:1]
	s_cbranch_execz .LBB0_1102
	s_waitcnt lgkmcnt(0)
	v_add_f32_e32 v0, v0, v130
	global_atomic_add_f32 v[166:167], v0, off offset:64

;     DEVI void operator()(f32x4 (&acc)[2][2][4][2], const Unit& u, int wr, int wc, int fr, int fq) const {
;     ...
;             for (int mm = 0; mm < 2; ++mm) { const int r = row0 + ai * HALF + (mb + mm) * 16;
;                 const float* xi = (in_is_stream ? (const float*)xrow_out(p, r) : xrow_in(p, l, r)) + col0;
; #pragma unroll
;                 for (int bj = 0; bj < 2; ++bj)
; #pragma unroll
;                     for (int n = 0; n < 2; ++n) xv[mm][bj][n] = *(const f32x4*)(xi + bj * HALF + n * 16); }
.LBB0_1114:
	v_lshlrev_b64 v[132:133], 12, v[132:133]
	s_waitcnt lgkmcnt(0)
	v_lshl_add_u64 v[130:131], v[130:131], 0, v[132:133]
	v_lshl_add_u64 v[130:131], v[206:207], 2, v[130:131]
	global_load_dwordx4 v[158:161], v[130:131], off nt
	global_load_dwordx4 v[150:153], v[130:131], off offset:64 nt
	global_load_dwordx4 v[142:145], v[130:131], off offset:512 nt
	global_load_dwordx4 v[134:137], v[130:131], off offset:576 nt
	v_or_b32_e32 v162, 48, v208
	s_mov_b32 s2, 0x8000
	s_movk_i32 s6, 0x7fff
	v_cmp_gt_i32_e64 s[2:3], s2, v162
	v_cmp_lt_i32_e64 s[6:7], s6, v162
	s_and_b64 vcc, exec, s[34:35]
	s_mov_b64 s[38:39], -1
	s_cbranch_vccnz .LBB0_1120
	v_mov_b64_e32 v[130:131], s[22:23]
	s_and_saveexec_b64 s[38:39], s[6:7]
	s_xor_b64 s[38:39], exec, s[38:39]
	v_add_u32_e32 v0, 0xffff8030, v208
	v_mov_b64_e32 v[130:131], s[16:17]
	v_mov_b64_e32 v[132:133], v[0:1]
	s_andn2_saveexec_b64 s[38:39], s[38:39]
	v_ashrrev_i32_e32 v163, 31, v162
	v_mov_b64_e32 v[132:133], v[162:163]
	s_or_b64 exec, exec, s[38:39]
	s_mov_b64 s[38:39], 0

; DEVI unsigned cvt_pk_bf16(float lo, float hi) { unsigned r; asm volatile("v_cvt_pk_bf16_f32 %0, %1, %2" : "=v"(r) : "v"(lo), "v"(hi)); return r; }
;     DEVI void operator()(f32x4 (&acc)[2][2][4][2], const Unit& u, int wr, int wc, int fr, int fq) const {
;     ...
;             for (int mm = 0; mm < 2; ++mm) { const int r = row0 + ai * HALF + (mb + mm) * 16;
;                 const float* xi = (in_is_stream ? (const float*)xrow_out(p, r) : xrow_in(p, l, r)) + col0;
; #pragma unroll
;                 for (int bj = 0; bj < 2; ++bj)
; #pragma unroll
;                     for (int n = 0; n < 2; ++n) xv[mm][bj][n] = *(const f32x4*)(xi + bj * HALF + n * 16); }
; #pragma unroll
;             for (int mm = 0; mm < 2; ++mm) { const int m = mb + mm; const int r = row0 + ai * HALF + m * 16; float* xo = xrow_out(p, r) + col0;
;                 float ssp = 0.f;
; #pragma unroll
;                 for (int bj = 0; bj < 2; ++bj)
; #pragma unroll
;                     for (int n = 0; n < 2; ++n) { const f32x4 xn = xv[mm][bj][n] + gv[bj][n] * acc[ai][bj][m][n]; *(f32x4*)(xo + bj * HALF + n * 16) = xn;
;                         if (emit) { ssp += xn[0] * xn[0] + xn[1] * xn[1] + xn[2] * xn[2] + xn[3] * xn[3];
;                             const f32x4 ua = xn * av[bj][n]; u32x2 w; w.x = cvt_pk_bf16(ua[0], ua[1]); w.y = cvt_pk_bf16(ua[2], ua[3]);
;                             *(u32x2*)((bf16_t*)(p.ws + OFF_U2) + (size_t)r * DM + col0 + bj * HALF + n * 16) = w; } }
;                 if (emit) { ssp += __shfl_xor(ssp, 16); ssp += __shfl_xor(ssp, 32); if (fq == 0) atomicAdd((float*)(p.ws + OFF_SSQ2) + (size_t)l * RT_ + r, ssp); } }
.LBB0_1126:
	v_lshlrev_b64 v[132:133], 12, v[132:133]
	v_lshl_add_u64 v[130:131], v[130:131], 0, v[132:133]
	v_lshl_add_u64 v[130:131], v[130:131], 0, v[210:211]
	global_load_dwordx4 v[154:157], v[130:131], off nt
	global_load_dwordx4 v[146:149], v[130:131], off offset:64 nt
	global_load_dwordx4 v[138:141], v[130:131], off offset:512 nt
	s_nop 0
	global_load_dwordx4 v[130:133], v[130:131], off offset:576 nt
	v_add_u32_e32 v0, 0xffff8020, v208
	v_ashrrev_i32_e32 v165, 31, v164
	v_cndmask_b32_e64 v170, v0, v164, s[4:5]
	v_mov_b32_e32 v0, s17
	v_mov_b32_e32 v163, s23
	v_cndmask_b32_e64 v171, 0, v165, s[4:5]
	v_cndmask_b32_e64 v173, v0, v163, s[4:5]
	v_mov_b32_e32 v0, s16
	v_mov_b32_e32 v163, s22
	s_waitcnt vmcnt(7)
	v_pk_fma_f32 v[126:127], v[126:127], v[86:87], v[158:159]
	v_cndmask_b32_e64 v172, v0, v163, s[4:5]
	v_lshlrev_b64 v[170:171], 12, v[170:171]
	v_mul_f32_e32 v0, v127, v127
	v_lshl_add_u64 v[170:171], v[172:173], 0, v[170:171]
	v_pk_fma_f32 v[128:129], v[128:129], v[88:89], v[160:161]
	v_fmac_f32_e32 v0, v126, v126
	v_lshl_add_u64 v[170:171], v[170:171], 0, v[210:211]
	v_fmac_f32_e32 v0, v128, v128
	v_lshlrev_b64 v[164:165], 11, v[164:165]
	global_store_dwordx4 v[170:171], v[126:129], off nt
	v_fmac_f32_e32 v0, v129, v129
	s_waitcnt vmcnt(7)
	v_pk_fma_f32 v[122:123], v[122:123], v[74:75], v[150:151]
	v_pk_mul_f32 v[128:129], v[92:93], v[128:129]
	v_pk_mul_f32 v[126:127], v[90:91], v[126:127]
	v_pk_fma_f32 v[124:125], v[124:125], v[76:77], v[152:153]
	v_cvt_pk_bf16_f32 v126, v126, v127
	v_cvt_pk_bf16_f32 v127, v128, v129
	v_lshl_add_u64 v[128:129], s[24:25], 0, v[164:165]
	v_lshl_add_u64 v[128:129], v[206:207], 1, v[128:129]
	global_store_dwordx2 v[128:129], v[126:127], off
	v_mul_f32_e32 v126, v123, v123
	global_store_dwordx4 v[170:171], v[122:125], off offset:64 nt
	v_fmac_f32_e32 v126, v122, v122
	v_fmac_f32_e32 v126, v124, v124
	v_pk_mul_f32 v[122:123], v[78:79], v[122:123]
	s_waitcnt vmcnt(8)
	v_pk_fma_f32 v[118:119], v[118:119], v[66:67], v[142:143]
	v_cvt_pk_bf16_f32 v122, v122, v123
	v_fmac_f32_e32 v126, v125, v125
	v_pk_mul_f32 v[124:125], v[80:81], v[124:125]
	v_pk_fma_f32 v[120:121], v[120:121], v[68:69], v[144:145]
	v_cvt_pk_bf16_f32 v123, v124, v125
	global_store_dwordx2 v[128:129], v[122:123], off offset:32
	v_mul_f32_e32 v122, v119, v119
	v_fmac_f32_e32 v122, v118, v118
	v_fmac_f32_e32 v122, v120, v120
	v_add_f32_e32 v0, v0, v126
	global_store_dwordx4 v[170:171], v[118:121], off offset:512 nt
	v_fmac_f32_e32 v122, v121, v121
	v_add_f32_e32 v0, v0, v122
	v_pk_mul_f32 v[118:119], v[70:71], v[118:119]
	v_pk_mul_f32 v[120:121], v[72:73], v[120:121]
	v_cvt_pk_bf16_f32 v122, v118, v119
	s_waitcnt vmcnt(9)
	v_pk_fma_f32 v[118:119], v[116:117], v[60:61], v[136:137]
	v_pk_fma_f32 v[116:117], v[114:115], v[58:59], v[134:135]
	v_cvt_pk_bf16_f32 v123, v120, v121
	global_store_dwordx2 v[128:129], v[122:123], off offset:256
	global_store_dwordx4 v[170:171], v[116:119], off offset:576 nt
	v_mul_f32_e32 v114, v117, v117
	v_fmac_f32_e32 v114, v116, v116
	v_fmac_f32_e32 v114, v118, v118
	v_fmac_f32_e32 v114, v119, v119
	v_add_f32_e32 v0, v0, v114
	ds_bpermute_b32 v114, v168, v0
	v_pk_mul_f32 v[116:117], v[54:55], v[116:117]
	v_pk_mul_f32 v[118:119], v[56:57], v[118:119]
	v_cvt_pk_bf16_f32 v116, v116, v117
	s_waitcnt lgkmcnt(0)
	v_add_f32_e32 v0, v0, v114
	ds_bpermute_b32 v114, v169, v0
	v_cvt_pk_bf16_f32 v117, v118, v119
	global_store_dwordx2 v[128:129], v[116:117], off offset:288
	s_and_saveexec_b64 s[4:5], s[0:1]
	s_cbranch_execz .LBB0_1128
	s_waitcnt lgkmcnt(0)
	v_add_f32_e32 v0, v0, v114
	global_atomic_add_f32 v[166:167], v0, off offset:128
.LBB0_1128:
	s_or_b64 exec, exec, s[4:5]
	v_add_u32_e32 v0, 0xffff8030, v208
	v_ashrrev_i32_e32 v163, 31, v162
	s_waitcnt lgkmcnt(0)
	v_cndmask_b32_e64 v114, v0, v162, s[2:3]
	v_mov_b32_e32 v0, s17
	v_mov_b32_e32 v116, s23
	v_cndmask_b32_e64 v115, 0, v163, s[2:3]
	v_cndmask_b32_e64 v117, v0, v116, s[2:3]
	v_mov_b32_e32 v0, s16
	v_mov_b32_e32 v116, s22
	s_waitcnt vmcnt(11)
	v_pk_fma_f32 v[110:111], v[110:111], v[86:87], v[154:155]
	v_cndmask_b32_e64 v116, v0, v116, s[2:3]
	v_lshlrev_b64 v[114:115], 12, v[114:115]
	v_mul_f32_e32 v0, v111, v111
	v_lshl_add_u64 v[114:115], v[116:117], 0, v[114:115]
	v_pk_fma_f32 v[112:113], v[112:113], v[88:89], v[156:157]
	v_fmac_f32_e32 v0, v110, v110
	v_lshl_add_u64 v[114:115], v[206:207], 2, v[114:115]
	v_fmac_f32_e32 v0, v112, v112
	v_lshlrev_b64 v[116:117], 11, v[162:163]
	global_store_dwordx4 v[114:115], v[110:113], off nt
	v_fmac_f32_e32 v0, v113, v113
	s_waitcnt vmcnt(11)
	v_pk_fma_f32 v[106:107], v[106:107], v[74:75], v[146:147]
	v_pk_mul_f32 v[112:113], v[92:93], v[112:113]
	v_pk_mul_f32 v[110:111], v[90:91], v[110:111]
	v_pk_fma_f32 v[108:109], v[108:109], v[76:77], v[148:149]
	v_cvt_pk_bf16_f32 v110, v110, v111
	v_cvt_pk_bf16_f32 v111, v112, v113
	v_lshl_add_u64 v[112:113], s[24:25], 0, v[116:117]
	v_lshl_add_u64 v[112:113], v[206:207], 1, v[112:113]
	global_store_dwordx2 v[112:113], v[110:111], off
	v_mul_f32_e32 v110, v107, v107
	global_store_dwordx4 v[114:115], v[106:109], off offset:64 nt
	v_fmac_f32_e32 v110, v106, v106
	v_fmac_f32_e32 v110, v108, v108
	v_pk_mul_f32 v[106:107], v[78:79], v[106:107]
	s_waitcnt vmcnt(12)
	v_pk_fma_f32 v[102:103], v[102:103], v[66:67], v[138:139]
	v_cvt_pk_bf16_f32 v106, v106, v107
	v_fmac_f32_e32 v110, v109, v109
	v_pk_mul_f32 v[108:109], v[80:81], v[108:109]
	v_pk_fma_f32 v[104:105], v[104:105], v[68:69], v[140:141]
	v_cvt_pk_bf16_f32 v107, v108, v109
	global_store_dwordx2 v[112:113], v[106:107], off offset:32
	v_mul_f32_e32 v106, v103, v103
	v_fmac_f32_e32 v106, v102, v102
	v_fmac_f32_e32 v106, v104, v104
	v_add_f32_e32 v0, v0, v110
	global_store_dwordx4 v[114:115], v[102:105], off offset:512 nt
	v_fmac_f32_e32 v106, v105, v105
	v_add_f32_e32 v0, v0, v106
	v_pk_mul_f32 v[102:103], v[70:71], v[102:103]
	v_pk_mul_f32 v[104:105], v[72:73], v[104:105]
	v_cvt_pk_bf16_f32 v106, v102, v103
	s_waitcnt vmcnt(13)
	v_pk_fma_f32 v[102:103], v[100:101], v[60:61], v[132:133]
	v_pk_fma_f32 v[100:101], v[98:99], v[58:59], v[130:131]
	v_cvt_pk_bf16_f32 v107, v104, v105
	global_store_dwordx2 v[112:113], v[106:107], off offset:256
	global_store_dwordx4 v[114:115], v[100:103], off offset:576 nt
	v_mul_f32_e32 v98, v101, v101
	v_fmac_f32_e32 v98, v100, v100
	v_fmac_f32_e32 v98, v102, v102
	v_fmac_f32_e32 v98, v103, v103
	v_add_f32_e32 v0, v0, v98
	ds_bpermute_b32 v98, v168, v0
	v_pk_mul_f32 v[100:101], v[54:55], v[100:101]
	v_pk_mul_f32 v[102:103], v[56:57], v[102:103]
	v_cvt_pk_bf16_f32 v100, v100, v101
	s_waitcnt lgkmcnt(0)
	v_add_f32_e32 v0, v0, v98
	ds_bpermute_b32 v98, v169, v0
	v_cvt_pk_bf16_f32 v101, v102, v103
	global_store_dwordx2 v[112:113], v[100:101], off offset:288
	s_and_saveexec_b64 s[2:3], s[0:1]
	s_cbranch_execz .LBB0_1130
	s_waitcnt lgkmcnt(0)
	v_add_f32_e32 v0, v0, v98
	global_atomic_add_f32 v[166:167], v0, off offset:192

;     DEVI void operator()(f32x4 (&acc)[2][2][4][2], const Unit& u, int wr, int wc, int fr, int fq) const {
;     ...
;             for (int mm = 0; mm < 2; ++mm) { const int r = row0 + ai * HALF + (mb + mm) * 16;
;                 const float* xi = (in_is_stream ? (const float*)xrow_out(p, r) : xrow_in(p, l, r)) + col0;
; #pragma unroll
;                 for (int bj = 0; bj < 2; ++bj)
; #pragma unroll
;                     for (int n = 0; n < 2; ++n) xv[mm][bj][n] = *(const f32x4*)(xi + bj * HALF + n * 16); }
.LBB0_1142:
	v_lshlrev_b64 v[100:101], 12, v[100:101]
	s_waitcnt lgkmcnt(0)
	v_lshl_add_u64 v[98:99], v[98:99], 0, v[100:101]
	v_lshl_add_u64 v[98:99], v[206:207], 2, v[98:99]
	global_load_dwordx4 v[126:129], v[98:99], off nt
	global_load_dwordx4 v[118:121], v[98:99], off offset:64 nt
	global_load_dwordx4 v[110:113], v[98:99], off offset:512 nt
	global_load_dwordx4 v[102:105], v[98:99], off offset:576 nt
	s_movk_i32 s2, 0x7f70
	s_movk_i32 s6, 0x7f6f
	v_add_u32_e32 v130, 0x90, v208
	v_cmp_gt_i32_e64 s[2:3], s2, v208
	v_cmp_lt_i32_e64 s[6:7], s6, v208
	s_and_b64 vcc, exec, s[34:35]
	s_mov_b64 s[38:39], -1
	s_cbranch_vccnz .LBB0_1148
	v_mov_b64_e32 v[98:99], s[22:23]
	s_and_saveexec_b64 s[38:39], s[6:7]
	s_xor_b64 s[38:39], exec, s[38:39]
	v_add_u32_e32 v0, 0xffff8090, v208
	v_mov_b64_e32 v[98:99], s[16:17]
	v_mov_b64_e32 v[100:101], v[0:1]
	s_andn2_saveexec_b64 s[38:39], s[38:39]
	v_ashrrev_i32_e32 v131, 31, v130
	v_mov_b64_e32 v[100:101], v[130:131]
	s_or_b64 exec, exec, s[38:39]
	s_mov_b64 s[38:39], 0

; DEVI unsigned cvt_pk_bf16(float lo, float hi) { unsigned r; asm volatile("v_cvt_pk_bf16_f32 %0, %1, %2" : "=v"(r) : "v"(lo), "v"(hi)); return r; }
;     DEVI void operator()(f32x4 (&acc)[2][2][4][2], const Unit& u, int wr, int wc, int fr, int fq) const {
;     ...
;             for (int mm = 0; mm < 2; ++mm) { const int r = row0 + ai * HALF + (mb + mm) * 16;
;                 const float* xi = (in_is_stream ? (const float*)xrow_out(p, r) : xrow_in(p, l, r)) + col0;
; #pragma unroll
;                 for (int bj = 0; bj < 2; ++bj)
; #pragma unroll
;                     for (int n = 0; n < 2; ++n) xv[mm][bj][n] = *(const f32x4*)(xi + bj * HALF + n * 16); }
; #pragma unroll
;             for (int mm = 0; mm < 2; ++mm) { const int m = mb + mm; const int r = row0 + ai * HALF + m * 16; float* xo = xrow_out(p, r) + col0;
;                 float ssp = 0.f;
; #pragma unroll
;                 for (int bj = 0; bj < 2; ++bj)
; #pragma unroll
;                     for (int n = 0; n < 2; ++n) { const f32x4 xn = xv[mm][bj][n] + gv[bj][n] * acc[ai][bj][m][n]; *(f32x4*)(xo + bj * HALF + n * 16) = xn;
;                         if (emit) { ssp += xn[0] * xn[0] + xn[1] * xn[1] + xn[2] * xn[2] + xn[3] * xn[3];
;                             const f32x4 ua = xn * av[bj][n]; u32x2 w; w.x = cvt_pk_bf16(ua[0], ua[1]); w.y = cvt_pk_bf16(ua[2], ua[3]);
;                             *(u32x2*)((bf16_t*)(p.ws + OFF_U2) + (size_t)r * DM + col0 + bj * HALF + n * 16) = w; } }
;                 if (emit) { ssp += __shfl_xor(ssp, 16); ssp += __shfl_xor(ssp, 32); if (fq == 0) atomicAdd((float*)(p.ws + OFF_SSQ2) + (size_t)l * RT_ + r, ssp); } }
.LBB0_1154:
	v_lshlrev_b64 v[100:101], 12, v[100:101]
	v_lshl_add_u64 v[98:99], v[98:99], 0, v[100:101]
	v_lshl_add_u64 v[98:99], v[98:99], 0, v[210:211]
	global_load_dwordx4 v[122:125], v[98:99], off nt
	global_load_dwordx4 v[114:117], v[98:99], off offset:64 nt
	global_load_dwordx4 v[106:109], v[98:99], off offset:512 nt
	s_nop 0
	global_load_dwordx4 v[98:101], v[98:99], off offset:576 nt
	v_add_u32_e32 v0, 0xffff8080, v208
	v_ashrrev_i32_e32 v133, 31, v132
	v_cndmask_b32_e64 v134, v0, v132, s[4:5]
	v_mov_b32_e32 v0, s17
	v_mov_b32_e32 v131, s23
	v_cndmask_b32_e64 v135, 0, v133, s[4:5]
	v_cndmask_b32_e64 v137, v0, v131, s[4:5]
	v_mov_b32_e32 v0, s16
	v_mov_b32_e32 v131, s22
	s_waitcnt vmcnt(7)
	v_pk_fma_f32 v[94:95], v[94:95], v[86:87], v[126:127]
	v_cndmask_b32_e64 v136, v0, v131, s[4:5]
	v_lshlrev_b64 v[134:135], 12, v[134:135]
	v_mul_f32_e32 v0, v95, v95
	v_lshl_add_u64 v[134:135], v[136:137], 0, v[134:135]
	v_pk_fma_f32 v[96:97], v[96:97], v[88:89], v[128:129]
	v_fmac_f32_e32 v0, v94, v94
	v_lshl_add_u64 v[134:135], v[134:135], 0, v[210:211]
	v_fmac_f32_e32 v0, v96, v96
	v_lshlrev_b64 v[132:133], 11, v[132:133]
	global_store_dwordx4 v[134:135], v[94:97], off nt
	v_fmac_f32_e32 v0, v97, v97
	s_waitcnt vmcnt(7)
	v_pk_fma_f32 v[82:83], v[82:83], v[74:75], v[118:119]
	v_pk_mul_f32 v[96:97], v[92:93], v[96:97]
	v_pk_mul_f32 v[94:95], v[90:91], v[94:95]
	v_pk_fma_f32 v[84:85], v[84:85], v[76:77], v[120:121]
	v_cvt_pk_bf16_f32 v94, v94, v95
	v_cvt_pk_bf16_f32 v95, v96, v97
	v_lshl_add_u64 v[96:97], s[24:25], 0, v[132:133]
	v_lshl_add_u64 v[96:97], v[206:207], 1, v[96:97]
	global_store_dwordx2 v[96:97], v[94:95], off
	v_mul_f32_e32 v94, v83, v83
	global_store_dwordx4 v[134:135], v[82:85], off offset:64 nt
	v_fmac_f32_e32 v94, v82, v82
	v_fmac_f32_e32 v94, v84, v84
	v_pk_mul_f32 v[82:83], v[78:79], v[82:83]
	s_waitcnt vmcnt(8)
	v_pk_fma_f32 v[62:63], v[62:63], v[66:67], v[110:111]
	v_cvt_pk_bf16_f32 v82, v82, v83
	v_fmac_f32_e32 v94, v85, v85
	v_pk_mul_f32 v[84:85], v[80:81], v[84:85]
	v_pk_fma_f32 v[64:65], v[64:65], v[68:69], v[112:113]
	v_cvt_pk_bf16_f32 v83, v84, v85
	global_store_dwordx2 v[96:97], v[82:83], off offset:32
	v_mul_f32_e32 v82, v63, v63
	global_store_dwordx4 v[134:135], v[62:65], off offset:512 nt
	v_fmac_f32_e32 v82, v62, v62
	v_fmac_f32_e32 v82, v64, v64
	v_pk_mul_f32 v[62:63], v[70:71], v[62:63]
	v_add_f32_e32 v0, v0, v94
	v_cvt_pk_bf16_f32 v84, v62, v63
	s_waitcnt vmcnt(9)
	v_pk_fma_f32 v[62:63], v[50:51], v[58:59], v[102:103]
	v_fmac_f32_e32 v82, v65, v65
	v_mul_f32_e32 v50, v63, v63
	v_add_f32_e32 v0, v0, v82
	v_pk_mul_f32 v[82:83], v[72:73], v[64:65]
	v_pk_fma_f32 v[64:65], v[52:53], v[60:61], v[104:105]
	v_fmac_f32_e32 v50, v62, v62
	v_fmac_f32_e32 v50, v64, v64
	v_fmac_f32_e32 v50, v65, v65
	v_add_f32_e32 v0, v0, v50
	ds_bpermute_b32 v50, v168, v0
	v_cvt_pk_bf16_f32 v85, v82, v83
	global_store_dwordx2 v[96:97], v[84:85], off offset:256
	global_store_dwordx4 v[134:135], v[62:65], off offset:576 nt
	v_pk_mul_f32 v[52:53], v[56:57], v[64:65]
	s_waitcnt lgkmcnt(0)
	v_add_f32_e32 v0, v0, v50
	ds_bpermute_b32 v50, v169, v0
	v_pk_mul_f32 v[62:63], v[54:55], v[62:63]
	s_nop 0
	v_cvt_pk_bf16_f32 v62, v62, v63
	v_cvt_pk_bf16_f32 v63, v52, v53
	global_store_dwordx2 v[96:97], v[62:63], off offset:288
	s_and_saveexec_b64 s[4:5], s[0:1]
	s_cbranch_execz .LBB0_1156
	s_waitcnt lgkmcnt(0)
	v_add_f32_e32 v0, v0, v50
	global_atomic_add_f32 v[166:167], v0, off offset:512
.LBB0_1156:
	s_or_b64 exec, exec, s[4:5]
	v_add_u32_e32 v0, 0xffff8090, v208
	v_ashrrev_i32_e32 v131, 31, v130
	s_waitcnt lgkmcnt(0)
	v_cndmask_b32_e64 v50, v0, v130, s[2:3]
	v_mov_b32_e32 v0, s17
	v_mov_b32_e32 v52, s23
	v_cndmask_b32_e64 v51, 0, v131, s[2:3]
	v_cndmask_b32_e64 v53, v0, v52, s[2:3]
	v_mov_b32_e32 v0, s16
	v_mov_b32_e32 v52, s22
	s_waitcnt vmcnt(11)
	v_pk_fma_f32 v[46:47], v[46:47], v[86:87], v[122:123]
	v_cndmask_b32_e64 v52, v0, v52, s[2:3]
	v_lshlrev_b64 v[50:51], 12, v[50:51]
	v_mul_f32_e32 v0, v47, v47
	v_lshl_add_u64 v[50:51], v[52:53], 0, v[50:51]
	v_pk_fma_f32 v[48:49], v[48:49], v[88:89], v[124:125]
	v_fmac_f32_e32 v0, v46, v46
	v_lshl_add_u64 v[50:51], v[206:207], 2, v[50:51]
	v_fmac_f32_e32 v0, v48, v48
	v_lshlrev_b64 v[52:53], 11, v[130:131]
	global_store_dwordx4 v[50:51], v[46:49], off nt
	v_fmac_f32_e32 v0, v49, v49
	s_waitcnt vmcnt(11)
	v_pk_fma_f32 v[42:43], v[42:43], v[74:75], v[114:115]
	v_pk_mul_f32 v[48:49], v[92:93], v[48:49]
	v_pk_mul_f32 v[46:47], v[90:91], v[46:47]
	v_pk_fma_f32 v[44:45], v[44:45], v[76:77], v[116:117]
	v_cvt_pk_bf16_f32 v46, v46, v47
	v_cvt_pk_bf16_f32 v47, v48, v49
	v_lshl_add_u64 v[48:49], s[24:25], 0, v[52:53]
	v_lshl_add_u64 v[48:49], v[206:207], 1, v[48:49]
	global_store_dwordx2 v[48:49], v[46:47], off
	v_mul_f32_e32 v46, v43, v43
	global_store_dwordx4 v[50:51], v[42:45], off offset:64 nt
	v_fmac_f32_e32 v46, v42, v42
	v_fmac_f32_e32 v46, v44, v44
	v_pk_mul_f32 v[42:43], v[78:79], v[42:43]
	s_waitcnt vmcnt(12)
	v_pk_fma_f32 v[38:39], v[38:39], v[66:67], v[106:107]
	v_cvt_pk_bf16_f32 v42, v42, v43
	v_fmac_f32_e32 v46, v45, v45
	v_pk_mul_f32 v[44:45], v[80:81], v[44:45]
	v_pk_fma_f32 v[40:41], v[40:41], v[68:69], v[108:109]
	v_cvt_pk_bf16_f32 v43, v44, v45
	global_store_dwordx2 v[48:49], v[42:43], off offset:32
	v_mul_f32_e32 v42, v39, v39
	v_fmac_f32_e32 v42, v38, v38
	v_fmac_f32_e32 v42, v40, v40
	v_add_f32_e32 v0, v0, v46
	global_store_dwordx4 v[50:51], v[38:41], off offset:512 nt
	v_fmac_f32_e32 v42, v41, v41
	v_add_f32_e32 v0, v0, v42
	v_pk_mul_f32 v[38:39], v[70:71], v[38:39]
	v_pk_mul_f32 v[40:41], v[72:73], v[40:41]
	v_cvt_pk_bf16_f32 v42, v38, v39
	s_waitcnt vmcnt(13)
	v_pk_fma_f32 v[38:39], v[36:37], v[60:61], v[100:101]
	v_pk_fma_f32 v[36:37], v[34:35], v[58:59], v[98:99]
	v_cvt_pk_bf16_f32 v43, v40, v41
	global_store_dwordx2 v[48:49], v[42:43], off offset:256
	global_store_dwordx4 v[50:51], v[36:39], off offset:576 nt
	v_mul_f32_e32 v34, v37, v37
	v_fmac_f32_e32 v34, v36, v36
	v_fmac_f32_e32 v34, v38, v38
	v_fmac_f32_e32 v34, v39, v39
	v_add_f32_e32 v0, v0, v34
	ds_bpermute_b32 v34, v168, v0
	v_pk_mul_f32 v[36:37], v[54:55], v[36:37]
	v_pk_mul_f32 v[38:39], v[56:57], v[38:39]
	v_cvt_pk_bf16_f32 v36, v36, v37
	s_waitcnt lgkmcnt(0)
	v_add_f32_e32 v0, v0, v34
	ds_bpermute_b32 v34, v169, v0
	v_cvt_pk_bf16_f32 v37, v38, v39
	global_store_dwordx2 v[48:49], v[36:37], off offset:288
	s_and_saveexec_b64 s[2:3], s[0:1]
	s_cbranch_execz .LBB0_1158
	s_waitcnt lgkmcnt(0)
	v_add_f32_e32 v0, v0, v34
	global_atomic_add_f32 v[166:167], v0, off offset:576

;     DEVI void operator()(f32x4 (&acc)[2][2][4][2], const Unit& u, int wr, int wc, int fr, int fq) const {
;     ...
;             for (int mm = 0; mm < 2; ++mm) { const int r = row0 + ai * HALF + (mb + mm) * 16;
;                 const float* xi = (in_is_stream ? (const float*)xrow_out(p, r) : xrow_in(p, l, r)) + col0;
; #pragma unroll
;                 for (int bj = 0; bj < 2; ++bj)
; #pragma unroll
;                     for (int n = 0; n < 2; ++n) xv[mm][bj][n] = *(const f32x4*)(xi + bj * HALF + n * 16); }
.LBB0_1170:
	v_lshlrev_b64 v[36:37], 12, v[36:37]
	s_waitcnt lgkmcnt(0)
	v_lshl_add_u64 v[34:35], v[34:35], 0, v[36:37]
	v_lshl_add_u64 v[34:35], v[206:207], 2, v[34:35]
	global_load_dwordx4 v[94:97], v[34:35], off nt
	global_load_dwordx4 v[62:65], v[34:35], off offset:64 nt
	global_load_dwordx4 v[46:49], v[34:35], off offset:512 nt
	global_load_dwordx4 v[38:41], v[34:35], off offset:576 nt
	s_movk_i32 s2, 0x7f50
	s_movk_i32 s6, 0x7f4f
	v_add_u32_e32 v98, 0xb0, v208
	v_cmp_gt_i32_e64 s[2:3], s2, v208
	v_cmp_lt_i32_e64 s[6:7], s6, v208
	s_and_b64 vcc, exec, s[34:35]
	s_mov_b64 s[38:39], -1
	s_cbranch_vccnz .LBB0_1176
	v_mov_b64_e32 v[34:35], s[22:23]
	s_and_saveexec_b64 s[38:39], s[6:7]
	s_xor_b64 s[38:39], exec, s[38:39]
	v_add_u32_e32 v0, 0xffff80b0, v208
	v_mov_b64_e32 v[34:35], s[16:17]
	v_mov_b64_e32 v[36:37], v[0:1]
	s_andn2_saveexec_b64 s[38:39], s[38:39]
	v_ashrrev_i32_e32 v99, 31, v98
	v_mov_b64_e32 v[36:37], v[98:99]
	s_or_b64 exec, exec, s[38:39]
	s_mov_b64 s[38:39], 0

; DEVI unsigned cvt_pk_bf16(float lo, float hi) { unsigned r; asm volatile("v_cvt_pk_bf16_f32 %0, %1, %2" : "=v"(r) : "v"(lo), "v"(hi)); return r; }
;     DEVI void operator()(f32x4 (&acc)[2][2][4][2], const Unit& u, int wr, int wc, int fr, int fq) const {
;     ...
;             for (int mm = 0; mm < 2; ++mm) { const int r = row0 + ai * HALF + (mb + mm) * 16;
;                 const float* xi = (in_is_stream ? (const float*)xrow_out(p, r) : xrow_in(p, l, r)) + col0;
; #pragma unroll
;                 for (int bj = 0; bj < 2; ++bj)
; #pragma unroll
;                     for (int n = 0; n < 2; ++n) xv[mm][bj][n] = *(const f32x4*)(xi + bj * HALF + n * 16); }
; #pragma unroll
;             for (int mm = 0; mm < 2; ++mm) { const int m = mb + mm; const int r = row0 + ai * HALF + m * 16; float* xo = xrow_out(p, r) + col0;
;                 float ssp = 0.f;
; #pragma unroll
;                 for (int bj = 0; bj < 2; ++bj)
; #pragma unroll
;                     for (int n = 0; n < 2; ++n) { const f32x4 xn = xv[mm][bj][n] + gv[bj][n] * acc[ai][bj][m][n]; *(f32x4*)(xo + bj * HALF + n * 16) = xn;
;                         if (emit) { ssp += xn[0] * xn[0] + xn[1] * xn[1] + xn[2] * xn[2] + xn[3] * xn[3];
;                             const f32x4 ua = xn * av[bj][n]; u32x2 w; w.x = cvt_pk_bf16(ua[0], ua[1]); w.y = cvt_pk_bf16(ua[2], ua[3]);
;                             *(u32x2*)((bf16_t*)(p.ws + OFF_U2) + (size_t)r * DM + col0 + bj * HALF + n * 16) = w; } }
;                 if (emit) { ssp += __shfl_xor(ssp, 16); ssp += __shfl_xor(ssp, 32); if (fq == 0) atomicAdd((float*)(p.ws + OFF_SSQ2) + (size_t)l * RT_ + r, ssp); } }
.LBB0_1182:
	v_lshlrev_b64 v[36:37], 12, v[36:37]
	v_lshl_add_u64 v[34:35], v[34:35], 0, v[36:37]
	v_lshl_add_u64 v[34:35], v[34:35], 0, v[210:211]
	global_load_dwordx4 v[82:85], v[34:35], off nt
	global_load_dwordx4 v[50:53], v[34:35], off offset:64 nt
	global_load_dwordx4 v[42:45], v[34:35], off offset:512 nt
	s_nop 0
	global_load_dwordx4 v[34:37], v[34:35], off offset:576 nt
	v_add_u32_e32 v0, 0xffff80a0, v208
	v_ashrrev_i32_e32 v101, 31, v100
	v_cndmask_b32_e64 v102, v0, v100, s[4:5]
	v_mov_b32_e32 v0, s17
	v_mov_b32_e32 v99, s23
	v_cndmask_b32_e64 v103, 0, v101, s[4:5]
	v_cndmask_b32_e64 v105, v0, v99, s[4:5]
	v_mov_b32_e32 v0, s16
	v_mov_b32_e32 v99, s22
	s_waitcnt vmcnt(7)
	v_pk_fma_f32 v[30:31], v[30:31], v[86:87], v[94:95]
	v_cndmask_b32_e64 v104, v0, v99, s[4:5]
	v_lshlrev_b64 v[102:103], 12, v[102:103]
	v_mul_f32_e32 v0, v31, v31
	v_lshl_add_u64 v[102:103], v[104:105], 0, v[102:103]
	v_pk_fma_f32 v[32:33], v[32:33], v[88:89], v[96:97]
	v_fmac_f32_e32 v0, v30, v30
	v_lshl_add_u64 v[102:103], v[102:103], 0, v[210:211]
	v_fmac_f32_e32 v0, v32, v32
	v_lshlrev_b64 v[100:101], 11, v[100:101]
	global_store_dwordx4 v[102:103], v[30:33], off nt
	v_fmac_f32_e32 v0, v33, v33
	s_waitcnt vmcnt(7)
	v_pk_fma_f32 v[26:27], v[26:27], v[74:75], v[62:63]
	v_pk_mul_f32 v[32:33], v[92:93], v[32:33]
	v_pk_mul_f32 v[30:31], v[90:91], v[30:31]
	v_pk_fma_f32 v[28:29], v[28:29], v[76:77], v[64:65]
	v_cvt_pk_bf16_f32 v30, v30, v31
	v_cvt_pk_bf16_f32 v31, v32, v33
	v_lshl_add_u64 v[32:33], s[24:25], 0, v[100:101]
	v_lshl_add_u64 v[32:33], v[206:207], 1, v[32:33]
	global_store_dwordx2 v[32:33], v[30:31], off
	v_mul_f32_e32 v30, v27, v27
	global_store_dwordx4 v[102:103], v[26:29], off offset:64 nt
	v_fmac_f32_e32 v30, v26, v26
	v_fmac_f32_e32 v30, v28, v28
	v_pk_mul_f32 v[26:27], v[78:79], v[26:27]
	s_waitcnt vmcnt(8)
	v_pk_fma_f32 v[22:23], v[22:23], v[66:67], v[46:47]
	v_cvt_pk_bf16_f32 v26, v26, v27
	v_fmac_f32_e32 v30, v29, v29
	v_pk_mul_f32 v[28:29], v[80:81], v[28:29]
	v_pk_fma_f32 v[24:25], v[24:25], v[68:69], v[48:49]
	v_cvt_pk_bf16_f32 v27, v28, v29
	global_store_dwordx2 v[32:33], v[26:27], off offset:32
	v_mul_f32_e32 v26, v23, v23
	v_fmac_f32_e32 v26, v22, v22
	v_fmac_f32_e32 v26, v24, v24
	v_add_f32_e32 v0, v0, v30
	global_store_dwordx4 v[102:103], v[22:25], off offset:512 nt
	v_fmac_f32_e32 v26, v25, v25
	v_add_f32_e32 v0, v0, v26
	v_pk_mul_f32 v[22:23], v[70:71], v[22:23]
	v_pk_mul_f32 v[24:25], v[72:73], v[24:25]
	v_cvt_pk_bf16_f32 v26, v22, v23
	s_waitcnt vmcnt(9)
	v_pk_fma_f32 v[22:23], v[20:21], v[60:61], v[40:41]
	v_pk_fma_f32 v[20:21], v[18:19], v[58:59], v[38:39]
	v_cvt_pk_bf16_f32 v27, v24, v25
	global_store_dwordx2 v[32:33], v[26:27], off offset:256
	global_store_dwordx4 v[102:103], v[20:23], off offset:576 nt
	v_mul_f32_e32 v18, v21, v21
	v_fmac_f32_e32 v18, v20, v20
	v_fmac_f32_e32 v18, v22, v22
	v_fmac_f32_e32 v18, v23, v23
	v_add_f32_e32 v0, v0, v18
	ds_bpermute_b32 v18, v168, v0
	v_pk_mul_f32 v[20:21], v[54:55], v[20:21]
	v_pk_mul_f32 v[22:23], v[56:57], v[22:23]
	v_cvt_pk_bf16_f32 v20, v20, v21
	s_waitcnt lgkmcnt(0)
	v_add_f32_e32 v0, v0, v18
	ds_bpermute_b32 v18, v169, v0
	v_cvt_pk_bf16_f32 v21, v22, v23
	global_store_dwordx2 v[32:33], v[20:21], off offset:288
	s_and_saveexec_b64 s[4:5], s[0:1]
	s_cbranch_execz .LBB0_1184
	s_waitcnt lgkmcnt(0)
	v_add_f32_e32 v0, v0, v18
	global_atomic_add_f32 v[166:167], v0, off offset:640
.LBB0_1184:
	s_or_b64 exec, exec, s[4:5]
	v_add_u32_e32 v0, 0xffff80b0, v208
	v_ashrrev_i32_e32 v99, 31, v98
	s_waitcnt lgkmcnt(0)
	v_cndmask_b32_e64 v18, v0, v98, s[2:3]
	v_mov_b32_e32 v0, s17
	v_mov_b32_e32 v20, s23
	v_cndmask_b32_e64 v19, 0, v99, s[2:3]
	v_cndmask_b32_e64 v21, v0, v20, s[2:3]
	v_mov_b32_e32 v0, s16
	v_mov_b32_e32 v20, s22
	s_waitcnt vmcnt(11)
	v_pk_fma_f32 v[14:15], v[14:15], v[86:87], v[82:83]
	v_cndmask_b32_e64 v20, v0, v20, s[2:3]
	v_lshlrev_b64 v[18:19], 12, v[18:19]
	v_mul_f32_e32 v0, v15, v15
	v_lshl_add_u64 v[18:19], v[20:21], 0, v[18:19]
	v_pk_fma_f32 v[16:17], v[16:17], v[88:89], v[84:85]
	v_fmac_f32_e32 v0, v14, v14
	v_lshl_add_u64 v[18:19], v[206:207], 2, v[18:19]
	v_fmac_f32_e32 v0, v16, v16
	v_lshlrev_b64 v[20:21], 11, v[98:99]
	global_store_dwordx4 v[18:19], v[14:17], off nt
	v_fmac_f32_e32 v0, v17, v17
	s_waitcnt vmcnt(11)
	v_pk_fma_f32 v[10:11], v[10:11], v[74:75], v[50:51]
	v_pk_mul_f32 v[16:17], v[92:93], v[16:17]
	v_pk_mul_f32 v[14:15], v[90:91], v[14:15]
	v_pk_fma_f32 v[12:13], v[12:13], v[76:77], v[52:53]
	v_cvt_pk_bf16_f32 v14, v14, v15
	v_cvt_pk_bf16_f32 v15, v16, v17
	v_lshl_add_u64 v[16:17], s[24:25], 0, v[20:21]
	v_lshl_add_u64 v[16:17], v[206:207], 1, v[16:17]
	global_store_dwordx2 v[16:17], v[14:15], off
	v_mul_f32_e32 v14, v11, v11
	global_store_dwordx4 v[18:19], v[10:13], off offset:64 nt
	v_fmac_f32_e32 v14, v10, v10
	v_fmac_f32_e32 v14, v12, v12
	v_pk_mul_f32 v[10:11], v[78:79], v[10:11]
	s_waitcnt vmcnt(12)
	v_pk_fma_f32 v[6:7], v[6:7], v[66:67], v[42:43]
	v_cvt_pk_bf16_f32 v10, v10, v11
	v_fmac_f32_e32 v14, v13, v13
	v_pk_mul_f32 v[12:13], v[80:81], v[12:13]
	v_pk_fma_f32 v[8:9], v[8:9], v[68:69], v[44:45]
	v_cvt_pk_bf16_f32 v11, v12, v13
	global_store_dwordx2 v[16:17], v[10:11], off offset:32
	v_mul_f32_e32 v10, v7, v7
	v_fmac_f32_e32 v10, v6, v6
	v_fmac_f32_e32 v10, v8, v8
	v_add_f32_e32 v0, v0, v14
	global_store_dwordx4 v[18:19], v[6:9], off offset:512 nt
	v_fmac_f32_e32 v10, v9, v9
	v_add_f32_e32 v0, v0, v10
	v_pk_mul_f32 v[6:7], v[70:71], v[6:7]
	v_pk_mul_f32 v[8:9], v[72:73], v[8:9]
	v_cvt_pk_bf16_f32 v10, v6, v7
	s_waitcnt vmcnt(13)
	v_pk_fma_f32 v[6:7], v[4:5], v[60:61], v[36:37]
	v_pk_fma_f32 v[4:5], v[2:3], v[58:59], v[34:35]
	v_cvt_pk_bf16_f32 v11, v8, v9
	global_store_dwordx2 v[16:17], v[10:11], off offset:256
	global_store_dwordx4 v[18:19], v[4:7], off offset:576 nt
	v_mul_f32_e32 v2, v5, v5
	v_fmac_f32_e32 v2, v4, v4
	v_fmac_f32_e32 v2, v6, v6
	v_fmac_f32_e32 v2, v7, v7
	v_add_f32_e32 v0, v0, v2
	ds_bpermute_b32 v2, v168, v0
	v_pk_mul_f32 v[4:5], v[54:55], v[4:5]
	v_pk_mul_f32 v[6:7], v[56:57], v[6:7]
	v_cvt_pk_bf16_f32 v4, v4, v5
	s_waitcnt lgkmcnt(0)
	v_add_f32_e32 v0, v0, v2
	ds_bpermute_b32 v2, v169, v0
	v_cvt_pk_bf16_f32 v5, v6, v7
	global_store_dwordx2 v[16:17], v[4:5], off offset:288
	s_and_saveexec_b64 s[2:3], s[0:1]
	s_cbranch_execz .LBB0_1067
	s_waitcnt lgkmcnt(0)
	v_add_f32_e32 v0, v0, v2
	global_atomic_add_f32 v[166:167], v0, off offset:704
	s_branch .LBB0_1067

; DEVI const float* modrow(const Params& p, int l, int row) { const int bi = row < NLAT ? (row >> 11) : 16; return (const float*)(p.ws + OFF_MOD) + (size_t)(l * 17 + bi) * 6144; }
;     DEVI void operator()(f32x4 (&acc)[2][2][4][2], const Unit& u, int wr, int wc, int fr, int fq) const {
;         const int row0 = u.pm * BM + wr * 64 + fr, col0 = u.pn * BM + wc * 32 + 4 * fq;
;         const float* gr = modrow(p, l, u.pm * BM) + goff + col0;
;         f32x4 gv[2][2];
; #pragma unroll
;         for (int bj = 0; bj < 2; ++bj)
; #pragma unroll
;             for (int n = 0; n < 2; ++n) gv[bj][n] = *(const f32x4*)(gr + bj * HALF + n * 16);
;         f32x4 av[2][2];
;         if (emit) { const int bi = u.pm * BM < NLAT ? (u.pm * BM) >> 11 : 16; const float* ar = (const float*)(p.ws + OFF_A2) + (size_t)(l * 17 + bi) * 1024 + col0;
; #pragma unroll
;             for (int bj = 0; bj < 2; ++bj)
; #pragma unroll
;                 for (int n = 0; n < 2; ++n) av[bj][n] = *(const f32x4*)(ar + bj * HALF + n * 16); }
; #pragma unroll
;         for (int am = 0; am < 4; ++am) {
;             const int ai = am >> 1, mb = (am & 1) * 2;
;             f32x4 xv[2][2][2];
; #pragma unroll
;             for (int mm = 0; mm < 2; ++mm) { const int r = row0 + ai * HALF + (mb + mm) * 16;
;                 const float* xi = (in_is_stream ? (const float*)xrow_out(p, r) : xrow_in(p, l, r)) + col0;
; #pragma unroll
;                 for (int bj = 0; bj < 2; ++bj)
; #pragma unroll
;                     for (int n = 0; n < 2; ++n) xv[mm][bj][n] = *(const f32x4*)(xi + bj * HALF + n * 16); }
; #pragma unroll
;             for (int mm = 0; mm < 2; ++mm) { const int m = mb + mm; const int r = row0 + ai * HALF + m * 16; float* xo = xrow_out(p, r) + col0;
;                 float ssp = 0.f;
; #pragma unroll
;                 for (int bj = 0; bj < 2; ++bj)
; #pragma unroll
;                     for (int n = 0; n < 2; ++n) { const f32x4 xn = xv[mm][bj][n] + gv[bj][n] * acc[ai][bj][m][n]; *(f32x4*)(xo + bj * HALF + n * 16) = xn;
.Lzp_epi_4:
	s_lshl_b32 s3, s12, 8
	v_lshl_or_b32 v130, s0, 8, v156
	s_min_i32 s0, s3, 0x8000
	s_ashr_i32 s0, s0, 11
	s_add_i32 s0, s0, s51
	s_mul_hi_i32 s1, s0, 0x6000
	s_mulk_i32 s0, 0x6000
	s_add_u32 s0, s24, s0
	v_ashrrev_i32_e32 v131, 31, v130
	s_addc_u32 s1, s25, s1
	v_lshlrev_b64 v[152:153], 2, v[130:131]
	v_lshl_add_u64 v[138:139], s[0:1], 0, v[152:153]
	s_mov_b64 s[0:1], 0x1e085000
	v_lshl_add_u64 v[140:141], v[138:139], 0, s[0:1]
	s_mov_b32 s0, 0x1e085000
	v_add_u32_e32 v161, s3, v154
	s_mov_b32 s3, 0x8000
	v_add_co_u32_e32 v138, vcc, s0, v138
	v_add_u32_e32 v142, 0xffff8000, v161
	v_ashrrev_i32_e32 v143, 31, v161
	v_cmp_gt_i32_e64 s[0:1], s3, v161
	v_mov_b32_e32 v160, s17
	v_mov_b32_e32 v162, s23
	v_cndmask_b32_e64 v143, 0, v143, s[0:1]
	v_cndmask_b32_e64 v142, v142, v161, s[0:1]
	v_mov_b32_e32 v158, s16
	v_mov_b32_e32 v159, s22
	v_cndmask_b32_e64 v145, v160, v162, s[0:1]
	v_cndmask_b32_e64 v144, v158, v159, s[0:1]
	v_lshlrev_b64 v[142:143], 12, v[142:143]
	v_lshl_add_u64 v[142:143], v[144:145], 0, v[142:143]
	v_lshl_add_u64 v[200:201], v[142:143], 0, v[152:153]
	v_or_b32_e32 v142, 16, v161
	v_add_u32_e32 v144, 0xffff8010, v161
	v_ashrrev_i32_e32 v143, 31, v142
	v_cmp_gt_i32_e64 s[0:1], s3, v142
	v_addc_co_u32_e32 v139, vcc, 0, v139, vcc
	s_nop 0
	v_cndmask_b32_e64 v143, 0, v143, s[0:1]
	v_cndmask_b32_e64 v142, v144, v142, s[0:1]
	v_cndmask_b32_e64 v145, v160, v162, s[0:1]
	v_cndmask_b32_e64 v144, v158, v159, s[0:1]
	v_lshlrev_b64 v[142:143], 12, v[142:143]
	v_lshl_add_u64 v[142:143], v[144:145], 0, v[142:143]
	v_lshl_add_u64 v[202:203], v[142:143], 0, v[152:153]
	global_load_dwordx4 v[134:137], v[140:141], off offset:64
	global_load_dwordx4 v[130:133], v[140:141], off offset:512
	global_load_dwordx4 v[164:167], v[200:201], off nt
	global_load_dwordx4 v[168:171], v[200:201], off offset:64 nt
	global_load_dwordx4 v[172:175], v[200:201], off offset:512 nt
	global_load_dwordx4 v[176:179], v[202:203], off offset:64 nt
	global_load_dwordx4 v[180:183], v[202:203], off offset:512 nt
	global_load_dwordx4 v[142:145], v[138:139], off
	s_nop 0
	global_load_dwordx4 v[138:141], v[140:141], off offset:576
	s_nop 0
	global_load_dwordx4 v[184:187], v[200:201], off offset:576 nt
	global_load_dwordx4 v[188:191], v[202:203], off nt
	global_load_dwordx4 v[192:195], v[202:203], off offset:576 nt
	v_or_b32_e32 v163, 32, v161
	v_add_u32_e32 v199, 0xffff8020, v161
	v_ashrrev_i32_e32 v204, 31, v163
	v_cmp_gt_i32_e32 vcc, s3, v163
	s_movk_i32 s0, 0x7f80
	s_mov_b32 s12, s4
	v_cndmask_b32_e32 v205, 0, v204, vcc
	v_cndmask_b32_e32 v204, v199, v163, vcc
	v_cndmask_b32_e32 v207, v160, v162, vcc
	v_cndmask_b32_e32 v206, v158, v159, vcc
	v_lshlrev_b64 v[204:205], 12, v[204:205]
	v_lshl_add_u64 v[204:205], v[206:207], 0, v[204:205]
	v_lshl_add_u64 v[204:205], v[204:205], 0, v[152:153]
	v_add_u32_e32 v163, 0xffff8080, v161
	s_mov_b64 s[30:31], s[10:11]
	s_mov_b64 s[28:29], s[8:9]
	s_movk_i32 s55, 0xc00
	s_waitcnt vmcnt(0)
	v_pk_fma_f32 v[124:125], v[124:125], v[144:145], v[166:167]
	v_pk_fma_f32 v[128:129], v[128:129], v[136:137], v[170:171]
	v_pk_fma_f32 v[126:127], v[126:127], v[134:135], v[168:169]
	v_pk_fma_f32 v[112:113], v[112:113], v[132:133], v[174:175]
	v_pk_fma_f32 v[110:111], v[110:111], v[130:131], v[172:173]
	v_pk_fma_f32 v[122:123], v[122:123], v[142:143], v[164:165]
	v_pk_fma_f32 v[98:99], v[98:99], v[138:139], v[192:193]
	v_pk_fma_f32 v[120:121], v[120:121], v[136:137], v[178:179]
	v_pk_fma_f32 v[118:119], v[118:119], v[134:135], v[176:177]
	v_pk_fma_f32 v[108:109], v[108:109], v[132:133], v[182:183]
	v_pk_fma_f32 v[106:107], v[106:107], v[130:131], v[180:181]
	global_store_dwordx4 v[200:201], v[126:129], off offset:64 nt
	global_store_dwordx4 v[200:201], v[110:113], off offset:512 nt
	v_pk_fma_f32 v[104:105], v[104:105], v[140:141], v[186:187]
	v_pk_fma_f32 v[102:103], v[102:103], v[138:139], v[184:185]
	v_pk_fma_f32 v[112:113], v[116:117], v[144:145], v[190:191]
	v_pk_fma_f32 v[110:111], v[114:115], v[142:143], v[188:189]
	v_pk_fma_f32 v[100:101], v[100:101], v[140:141], v[194:195]
	global_store_dwordx4 v[200:201], v[122:125], off nt
	global_store_dwordx4 v[200:201], v[102:105], off offset:576 nt
	global_store_dwordx4 v[202:203], v[110:113], off nt
	global_store_dwordx4 v[202:203], v[118:121], off offset:64 nt
	global_store_dwordx4 v[202:203], v[106:109], off offset:512 nt
	global_store_dwordx4 v[202:203], v[98:101], off offset:576 nt
	v_add_u32_e32 v116, 0xffff8030, v161
	global_load_dwordx4 v[100:103], v[204:205], off nt
	global_load_dwordx4 v[104:107], v[204:205], off offset:64 nt
	global_load_dwordx4 v[108:111], v[204:205], off offset:512 nt
	global_load_dwordx4 v[112:115], v[204:205], off offset:576 nt
	v_or_b32_e32 v98, 48, v161
	v_ashrrev_i32_e32 v99, 31, v98
	v_cmp_gt_i32_e32 vcc, s3, v98
	v_add_u32_e32 v170, 0x90, v161
	v_add_u32_e32 v172, 0xffff8090, v161
	v_cndmask_b32_e32 v99, 0, v99, vcc
	v_cndmask_b32_e32 v98, v116, v98, vcc
	v_cndmask_b32_e32 v117, v160, v162, vcc
	v_cndmask_b32_e32 v116, v158, v159, vcc
	v_lshlrev_b64 v[98:99], 12, v[98:99]
	v_lshl_add_u64 v[98:99], v[116:117], 0, v[98:99]
	v_lshl_add_u64 v[128:129], v[98:99], 0, v[152:153]
	global_load_dwordx4 v[116:119], v[128:129], off nt
	global_load_dwordx4 v[120:123], v[128:129], off offset:64 nt
	global_load_dwordx4 v[124:127], v[128:129], off offset:512 nt
	global_load_dwordx4 v[164:167], v[128:129], off offset:576 nt
	v_add_u32_e32 v98, 0x80, v161
	v_ashrrev_i32_e32 v99, 31, v98
	v_cmp_gt_i32_e32 vcc, s0, v161
	s_movk_i32 s0, 0x7f70
	v_ashrrev_i32_e32 v171, 31, v170
	v_cndmask_b32_e32 v99, 0, v99, vcc
	v_cndmask_b32_e32 v98, v163, v98, vcc
	v_cndmask_b32_e32 v169, v160, v162, vcc
	v_cndmask_b32_e32 v168, v158, v159, vcc
	v_cmp_gt_i32_e32 vcc, s0, v161
	v_lshlrev_b64 v[98:99], 12, v[98:99]
	v_lshl_add_u64 v[98:99], v[168:169], 0, v[98:99]
	v_cndmask_b32_e32 v171, 0, v171, vcc
	v_cndmask_b32_e32 v170, v172, v170, vcc
	v_cndmask_b32_e32 v173, v160, v162, vcc
	v_cndmask_b32_e32 v172, v158, v159, vcc
	v_lshl_add_u64 v[98:99], v[98:99], 0, v[152:153]
	s_movk_i32 s0, 0x7f60
	v_cmp_gt_i32_e32 vcc, s0, v161
	s_movk_i32 s0, 0x7f50
	s_waitcnt vmcnt(0)
;     DEVI void operator()(f32x4 (&acc)[2][2][4][2], const Unit& u, int wr, int wc, int fr, int fq) const {
;     ...
;             for (int mm = 0; mm < 2; ++mm) { const int r = row0 + ai * HALF + (mb + mm) * 16;
;                 const float* xi = (in_is_stream ? (const float*)xrow_out(p, r) : xrow_in(p, l, r)) + col0;
; #pragma unroll
;                 for (int bj = 0; bj < 2; ++bj)
; #pragma unroll
;                     for (int n = 0; n < 2; ++n) xv[mm][bj][n] = *(const f32x4*)(xi + bj * HALF + n * 16); }
; #pragma unroll
;             for (int mm = 0; mm < 2; ++mm) { const int m = mb + mm; const int r = row0 + ai * HALF + m * 16; float* xo = xrow_out(p, r) + col0;
;                 float ssp = 0.f;
; #pragma unroll
;                 for (int bj = 0; bj < 2; ++bj)
; #pragma unroll
;                     for (int n = 0; n < 2; ++n) { const f32x4 xn = xv[mm][bj][n] + gv[bj][n] * acc[ai][bj][m][n]; *(f32x4*)(xo + bj * HALF + n * 16) = xn;
	v_pk_fma_f32 v[96:97], v[96:97], v[144:145], v[102:103]
	v_pk_fma_f32 v[94:95], v[94:95], v[142:143], v[100:101]
	v_pk_fma_f32 v[78:79], v[78:79], v[130:131], v[108:109]
	v_pk_fma_f32 v[92:93], v[92:93], v[136:137], v[106:107]
	v_pk_fma_f32 v[90:91], v[90:91], v[134:135], v[104:105]
	v_pk_fma_f32 v[80:81], v[80:81], v[132:133], v[110:111]
	v_pk_fma_f32 v[76:77], v[76:77], v[140:141], v[114:115]
	v_pk_fma_f32 v[74:75], v[74:75], v[138:139], v[112:113]
	v_add_u32_e32 v102, 0xa0, v161
	v_add_u32_e32 v104, 0xffff80a0, v161
	v_add_u32_e32 v106, 0xb0, v161
	v_ashrrev_i32_e32 v103, 31, v102
	v_add_u32_e32 v108, 0xffff80b0, v161
	v_pk_fma_f32 v[88:89], v[88:89], v[144:145], v[118:119]
	v_pk_fma_f32 v[86:87], v[86:87], v[142:143], v[116:117]
	v_pk_fma_f32 v[84:85], v[84:85], v[136:137], v[122:123]
	v_pk_fma_f32 v[82:83], v[82:83], v[134:135], v[120:121]
	v_pk_fma_f32 v[72:73], v[72:73], v[132:133], v[126:127]
	v_pk_fma_f32 v[70:71], v[70:71], v[130:131], v[124:125]
	v_pk_fma_f32 v[68:69], v[68:69], v[140:141], v[166:167]
	v_pk_fma_f32 v[66:67], v[66:67], v[138:139], v[164:165]
	global_store_dwordx4 v[204:205], v[94:97], off nt
	global_store_dwordx4 v[204:205], v[90:93], off offset:64 nt
	global_store_dwordx4 v[204:205], v[78:81], off offset:512 nt
	global_store_dwordx4 v[204:205], v[74:77], off offset:576 nt
	global_store_dwordx4 v[128:129], v[86:89], off nt
	global_store_dwordx4 v[128:129], v[82:85], off offset:64 nt
	global_store_dwordx4 v[128:129], v[70:73], off offset:512 nt
	global_store_dwordx4 v[128:129], v[66:69], off offset:576 nt
	v_lshlrev_b64 v[78:79], 12, v[170:171]
	v_lshl_add_u64 v[82:83], v[172:173], 0, v[78:79]
	global_load_dwordx4 v[66:69], v[98:99], off nt
	global_load_dwordx4 v[70:73], v[98:99], off offset:64 nt
	global_load_dwordx4 v[74:77], v[98:99], off offset:512 nt
	global_load_dwordx4 v[78:81], v[98:99], off offset:576 nt
	v_lshl_add_u64 v[100:101], v[82:83], 0, v[152:153]
	global_load_dwordx4 v[82:85], v[100:101], off nt
	global_load_dwordx4 v[86:89], v[100:101], off offset:64 nt
	global_load_dwordx4 v[90:93], v[100:101], off offset:512 nt
	global_load_dwordx4 v[94:97], v[100:101], off offset:576 nt
	v_ashrrev_i32_e32 v107, 31, v106
	v_cndmask_b32_e32 v103, 0, v103, vcc
	v_cndmask_b32_e32 v102, v104, v102, vcc
	v_cndmask_b32_e32 v105, v160, v162, vcc
	v_cndmask_b32_e32 v104, v158, v159, vcc
	v_cmp_gt_i32_e32 vcc, s0, v161
	v_lshlrev_b64 v[102:103], 12, v[102:103]
	v_lshl_add_u64 v[102:103], v[104:105], 0, v[102:103]
	v_cndmask_b32_e32 v107, 0, v107, vcc
	v_cndmask_b32_e32 v106, v108, v106, vcc
	v_cndmask_b32_e32 v109, v160, v162, vcc
	v_cndmask_b32_e32 v108, v158, v159, vcc
	v_lshl_add_u64 v[102:103], v[102:103], 0, v[152:153]
	s_mov_b32 s0, s2
	s_and_b64 vcc, exec, s[6:7]
	s_waitcnt vmcnt(0)
	v_pk_fma_f32 v[64:65], v[64:65], v[144:145], v[68:69]
	v_pk_fma_f32 v[62:63], v[62:63], v[142:143], v[66:67]
	v_pk_fma_f32 v[46:47], v[46:47], v[130:131], v[74:75]
	v_pk_fma_f32 v[60:61], v[60:61], v[136:137], v[72:73]
	v_pk_fma_f32 v[58:59], v[58:59], v[134:135], v[70:71]
	v_pk_fma_f32 v[48:49], v[48:49], v[132:133], v[76:77]
	v_pk_fma_f32 v[44:45], v[44:45], v[140:141], v[80:81]
	v_pk_fma_f32 v[42:43], v[42:43], v[138:139], v[78:79]
	v_pk_fma_f32 v[56:57], v[56:57], v[144:145], v[84:85]
	v_pk_fma_f32 v[54:55], v[54:55], v[142:143], v[82:83]
	v_pk_fma_f32 v[52:53], v[52:53], v[136:137], v[88:89]
	v_pk_fma_f32 v[50:51], v[50:51], v[134:135], v[86:87]
	v_pk_fma_f32 v[40:41], v[40:41], v[132:133], v[92:93]
	v_pk_fma_f32 v[38:39], v[38:39], v[130:131], v[90:91]
	v_pk_fma_f32 v[36:37], v[36:37], v[140:141], v[96:97]
	v_pk_fma_f32 v[34:35], v[34:35], v[138:139], v[94:95]
	global_store_dwordx4 v[98:99], v[62:65], off nt
	global_store_dwordx4 v[98:99], v[58:61], off offset:64 nt
	global_store_dwordx4 v[98:99], v[46:49], off offset:512 nt
	global_store_dwordx4 v[98:99], v[42:45], off offset:576 nt
	global_store_dwordx4 v[100:101], v[54:57], off nt
	global_store_dwordx4 v[100:101], v[50:53], off offset:64 nt
	global_store_dwordx4 v[100:101], v[38:41], off offset:512 nt
	global_store_dwordx4 v[100:101], v[34:37], off offset:576 nt
	v_lshlrev_b64 v[46:47], 12, v[106:107]
	v_lshl_add_u64 v[50:51], v[108:109], 0, v[46:47]
	global_load_dwordx4 v[34:37], v[102:103], off nt
	global_load_dwordx4 v[38:41], v[102:103], off offset:64 nt
	v_lshl_add_u64 v[66:67], v[50:51], 0, v[152:153]
	global_load_dwordx4 v[42:45], v[102:103], off offset:512 nt
	global_load_dwordx4 v[46:49], v[102:103], off offset:576 nt
	global_load_dwordx4 v[50:53], v[66:67], off nt
	global_load_dwordx4 v[54:57], v[66:67], off offset:64 nt
	global_load_dwordx4 v[58:61], v[66:67], off offset:512 nt
	global_load_dwordx4 v[62:65], v[66:67], off offset:576 nt
	s_waitcnt vmcnt(0)
	v_pk_fma_f32 v[32:33], v[32:33], v[144:145], v[36:37]
	v_pk_fma_f32 v[30:31], v[30:31], v[142:143], v[34:35]
	v_pk_fma_f32 v[28:29], v[28:29], v[136:137], v[40:41]
	v_pk_fma_f32 v[26:27], v[26:27], v[134:135], v[38:39]
	v_pk_fma_f32 v[16:17], v[16:17], v[132:133], v[44:45]
	v_pk_fma_f32 v[14:15], v[14:15], v[130:131], v[42:43]
	v_pk_fma_f32 v[12:13], v[12:13], v[140:141], v[48:49]
	v_pk_fma_f32 v[10:11], v[10:11], v[138:139], v[46:47]
	v_pk_fma_f32 v[24:25], v[24:25], v[144:145], v[52:53]
	v_pk_fma_f32 v[22:23], v[22:23], v[142:143], v[50:51]
	v_pk_fma_f32 v[20:21], v[20:21], v[136:137], v[56:57]
	v_pk_fma_f32 v[18:19], v[18:19], v[134:135], v[54:55]
	v_pk_fma_f32 v[8:9], v[8:9], v[132:133], v[60:61]
	v_pk_fma_f32 v[6:7], v[6:7], v[130:131], v[58:59]
	v_pk_fma_f32 v[4:5], v[4:5], v[140:141], v[64:65]
	v_pk_fma_f32 v[2:3], v[2:3], v[138:139], v[62:63]
	global_store_dwordx4 v[102:103], v[30:33], off nt
	global_store_dwordx4 v[102:103], v[26:29], off offset:64 nt
	global_store_dwordx4 v[102:103], v[14:17], off offset:512 nt
	global_store_dwordx4 v[102:103], v[10:13], off offset:576 nt
	global_store_dwordx4 v[66:67], v[22:25], off nt
	global_store_dwordx4 v[66:67], v[18:21], off offset:64 nt
	global_store_dwordx4 v[66:67], v[6:9], off offset:512 nt
	global_store_dwordx4 v[66:67], v[2:5], off offset:576 nt
	s_cbranch_vccz .LBB0_1348
	s_branch .LBB0_1356
